# ada_partials item prologue: first two ada_w prefetch batches issued before the wait for the c load (counted vmcnt(16)) instead of after the second barrier; on top of the session-best version
# baseline (speedup 1.0000x reference)
; DI void ada_partials(const P& p, LAS unsigned char* L) {
;     ...
;     for (int item = blockIdx.x; item < 768; item += gridDim.x) {
;         const int l = item / 384, r = item % 384, cb = r / 16, ks = r % 16;
;         __syncthreads();
;         { const int b = tid >> 7, k = tid & 127; const float cv = p.c[b * DM + ks * 128 + k]; condl[tid] = cv * __builtin_amdgcn_rcpf(1.f + __expf(-cv)); }
;         __syncthreads();
;         const int col = cb * 512 + tid;
;         const float* w = p.ada_w + ((size_t)l * DM + ks * 128) * MODW + col;
;         float a0 = 0.f, a1 = 0.f, a2 = 0.f, a3 = 0.f;
; #pragma unroll 8
;         for (int k = 0; k < 128; ++k) { const float wv = w[(size_t)k * MODW]; a0 += condl[k] * wv; a1 += condl[128 + k] * wv; a2 += condl[256 + k] * wv; a3 += condl[384 + k] * wv; }
.LBB0_46:
	s_mul_hi_i32 s4, s19, 0x2aaaaaab
	s_lshr_b32 s5, s4, 31
	s_ashr_i32 s20, s4, 6
	s_add_i32 s20, s20, s5
	s_mul_i32 s4, s20, 0x180
	s_sub_i32 s4, s19, s4
	s_bfe_u32 s5, s4, 0x4001b
	s_add_i32 s5, s4, s5
	s_and_b32 s21, s5, 0xfff0
	s_sub_i32 s4, s4, s21
	s_sext_i32_i16 s21, s4
	s_lshl_b32 s4, s21, 7
	v_add_u32_e32 v0, s4, v9
	v_ashrrev_i32_e32 v1, 31, v0
	v_lshl_add_u64 v[0:1], v[0:1], 2, s[8:9]
	s_barrier
	global_load_dword v5, v[0:1], off
	s_sext_i32_i16 s5, s5
	s_lshl_b32 s5, s5, 5
	s_and_b32 s5, s5, 0xfffffe00
	s_mul_i32 s24, s20, 0x6000000
	v_add_u32_e32 v2, s5, v8
	s_mul_i32 s5, s21, 0x600000
	s_mul_hi_i32 s23, s20, 0x6000000
	s_mul_hi_i32 s4, s4, 0xc000
	s_add_u32 s5, s24, s5
	s_addc_u32 s23, s23, s4
	s_add_u32 s4, s3, s5
	v_mov_b32_e32 v0, 0
	v_ashrrev_i32_e32 v3, 31, v2
	s_addc_u32 s5, s12, s23
	s_movk_i32 s22, 0xfe00
	v_mov_b32_e32 v1, v0
	v_mov_b32_e32 v4, v0
	v_lshl_add_u64 v[6:7], v[2:3], 2, s[4:5]
	v_add_co_u32_e64 v14, s[4:5], s14, v6
	v_add_co_u32_e32 v12, vcc, 0xfffd0000, v6
	s_nop 0
	v_addc_co_u32_e64 v15, s[4:5], -1, v7, s[4:5]
	v_add_co_u32_e64 v16, s[4:5], s15, v6
	global_load_dword v44, v[6:7], off
	s_nop 0
	v_addc_co_u32_e64 v17, s[4:5], -1, v7, s[4:5]
	v_add_co_u32_e64 v18, s[4:5], s16, v6
	v_addc_co_u32_e32 v13, vcc, -1, v7, vcc
	s_nop 0
	v_addc_co_u32_e64 v19, s[4:5], -1, v7, s[4:5]
	v_add_co_u32_e64 v20, s[4:5], s13, v6
	s_nop 1
	v_addc_co_u32_e64 v21, s[4:5], 0, v7, s[4:5]
	v_add_co_u32_e64 v22, s[4:5], s17, v6
	s_nop 1
	v_addc_co_u32_e64 v23, s[4:5], 0, v7, s[4:5]
	v_add_co_u32_e64 v24, s[4:5], s18, v6
	s_nop 1
	v_addc_co_u32_e64 v25, s[4:5], 0, v7, s[4:5]
	global_load_dword v46, v[14:15], off
	global_load_dword v48, v[16:17], off
	global_load_dword v50, v[12:13], off
	global_load_dword v52, v[18:19], off
	global_load_dword v54, v[20:21], off
	global_load_dword v56, v[22:23], off
	global_load_dword v58, v[24:25], off
	v_lshl_add_u64 v[6:7], v[6:7], 0, s[10:11]
	v_add_co_u32_e64 v14, s[4:5], s14, v6
	v_add_co_u32_e32 v12, vcc, 0xfffd0000, v6
	s_nop 0
	v_addc_co_u32_e64 v15, s[4:5], -1, v7, s[4:5]
	v_add_co_u32_e64 v16, s[4:5], s15, v6
	global_load_dword v64, v[6:7], off
	s_nop 0
	v_addc_co_u32_e64 v17, s[4:5], -1, v7, s[4:5]
	v_add_co_u32_e64 v18, s[4:5], s16, v6
	v_addc_co_u32_e32 v13, vcc, -1, v7, vcc
	s_nop 0
	v_addc_co_u32_e64 v19, s[4:5], -1, v7, s[4:5]
	v_add_co_u32_e64 v20, s[4:5], s13, v6
	s_nop 1
	v_addc_co_u32_e64 v21, s[4:5], 0, v7, s[4:5]
	v_add_co_u32_e64 v22, s[4:5], s17, v6
	s_nop 1
	v_addc_co_u32_e64 v23, s[4:5], 0, v7, s[4:5]
	v_add_co_u32_e64 v24, s[4:5], s18, v6
	s_nop 1
	v_addc_co_u32_e64 v25, s[4:5], 0, v7, s[4:5]
	global_load_dword v66, v[14:15], off
	global_load_dword v68, v[16:17], off
	global_load_dword v70, v[12:13], off
	global_load_dword v72, v[18:19], off
	global_load_dword v74, v[20:21], off
	global_load_dword v76, v[22:23], off
	global_load_dword v78, v[24:25], off
	v_lshl_add_u64 v[6:7], v[6:7], 0, s[10:11]
	s_waitcnt vmcnt(16)
	v_mul_f32_e32 v96, 0xbfb8aa3b, v5
	v_exp_f32_e32 v96, v96
	s_nop 0
	v_add_f32_e32 v96, 1.0, v96
	v_rcp_f32_e32 v97, v96
	s_nop 0
	v_mul_f32_e32 v5, v5, v97
	ds_write_b32 v10, v5
	v_mov_b32_e32 v5, v0
	s_waitcnt lgkmcnt(0)
	s_barrier
	v_mov_b32_e32 v11, 0x20000
	v_add_co_u32_e64 v14, s[4:5], s14, v6
	v_add_co_u32_e32 v12, vcc, 0xfffd0000, v6
	s_nop 0
	v_addc_co_u32_e64 v15, s[4:5], -1, v7, s[4:5]
	v_add_co_u32_e64 v16, s[4:5], s15, v6
	global_load_dword v80, v[6:7], off
	s_nop 0
	v_addc_co_u32_e64 v17, s[4:5], -1, v7, s[4:5]
	v_add_co_u32_e64 v18, s[4:5], s16, v6
	v_addc_co_u32_e32 v13, vcc, -1, v7, vcc
	s_nop 0
	v_addc_co_u32_e64 v19, s[4:5], -1, v7, s[4:5]
	v_add_co_u32_e64 v20, s[4:5], s13, v6
	s_nop 1
	v_addc_co_u32_e64 v21, s[4:5], 0, v7, s[4:5]
	v_add_co_u32_e64 v22, s[4:5], s17, v6
	s_nop 1
	v_addc_co_u32_e64 v23, s[4:5], 0, v7, s[4:5]
	v_add_co_u32_e64 v24, s[4:5], s18, v6
	s_nop 1
	v_addc_co_u32_e64 v25, s[4:5], 0, v7, s[4:5]
	global_load_dword v82, v[14:15], off
	global_load_dword v84, v[16:17], off
	global_load_dword v86, v[12:13], off
	global_load_dword v88, v[18:19], off
	global_load_dword v90, v[20:21], off
	global_load_dword v92, v[22:23], off
	global_load_dword v94, v[24:25], off
	v_lshl_add_u64 v[6:7], v[6:7], 0, s[10:11]
	ds_read_b128 v[12:15], v11 offset:0
	ds_read_b128 v[16:19], v11 offset:512
	ds_read_b128 v[20:23], v11 offset:1024
	ds_read_b128 v[24:27], v11 offset:1536
	ds_read_b128 v[28:31], v11 offset:16
	ds_read_b128 v[32:35], v11 offset:528
	ds_read_b128 v[36:39], v11 offset:1040
	ds_read_b128 v[40:43], v11 offset:1552
	s_waitcnt lgkmcnt(6)
	v_mov_b32_e32 v60, v16
	v_mov_b32_e32 v61, v12
	s_waitcnt lgkmcnt(4)
	v_mov_b32_e32 v62, v24
	v_mov_b32_e32 v63, v20
	v_mov_b32_e32 v12, v17
	v_mov_b32_e32 v20, v25
	v_mov_b32_e32 v16, v18
	v_mov_b32_e32 v17, v14
	v_mov_b32_e32 v14, v19
	v_mov_b32_e32 v18, v26
	v_mov_b32_e32 v19, v22
	v_mov_b32_e32 v22, v27
	s_waitcnt lgkmcnt(2)
	v_mov_b32_e32 v24, v32
	v_mov_b32_e32 v25, v28
	s_waitcnt lgkmcnt(0)
	v_mov_b32_e32 v26, v40
	v_mov_b32_e32 v27, v36
	v_mov_b32_e32 v28, v33
	v_mov_b32_e32 v36, v41
	v_mov_b32_e32 v32, v34
	v_mov_b32_e32 v33, v30
	v_mov_b32_e32 v30, v35
	v_mov_b32_e32 v34, v42
	v_mov_b32_e32 v35, v38
	v_mov_b32_e32 v38, v43
	s_waitcnt vmcnt(20)
	v_pk_fma_f32 v[4:5], v[50:51], v[60:61], v[4:5] op_sel_hi:[0,1,1]
	v_pk_fma_f32 v[0:1], v[50:51], v[62:63], v[0:1] op_sel_hi:[0,1,1]
	v_pk_fma_f32 v[4:5], v[46:47], v[12:13], v[4:5] op_sel_hi:[0,1,1]
	v_pk_fma_f32 v[0:1], v[46:47], v[20:21], v[0:1] op_sel_hi:[0,1,1]
	v_pk_fma_f32 v[4:5], v[48:49], v[16:17], v[4:5] op_sel_hi:[0,1,1]
	v_pk_fma_f32 v[0:1], v[48:49], v[18:19], v[0:1] op_sel_hi:[0,1,1]
	s_waitcnt vmcnt(19)
; DI void ada_partials(const P& p, LAS unsigned char* L) {
;     ...
;         float a0 = 0.f, a1 = 0.f, a2 = 0.f, a3 = 0.f;
; #pragma unroll 8
;         for (int k = 0; k < 128; ++k) { const float wv = w[(size_t)k * MODW]; a0 += condl[k] * wv; a1 += condl[128 + k] * wv; a2 += condl[256 + k] * wv; a3 += condl[384 + k] * wv; }
	v_pk_fma_f32 v[4:5], v[52:53], v[14:15], v[4:5] op_sel_hi:[0,1,1]
	v_pk_fma_f32 v[0:1], v[52:53], v[22:23], v[0:1] op_sel_hi:[0,1,1]
	v_pk_fma_f32 v[4:5], v[44:45], v[24:25], v[4:5] op_sel_hi:[0,1,1]
	v_pk_fma_f32 v[0:1], v[44:45], v[26:27], v[0:1] op_sel_hi:[0,1,1]
	s_waitcnt vmcnt(18)
	v_pk_fma_f32 v[4:5], v[54:55], v[28:29], v[4:5] op_sel_hi:[0,1,1]
	v_pk_fma_f32 v[0:1], v[54:55], v[36:37], v[0:1] op_sel_hi:[0,1,1]
	s_waitcnt vmcnt(17)
	v_pk_fma_f32 v[4:5], v[56:57], v[32:33], v[4:5] op_sel_hi:[0,1,1]
	v_pk_fma_f32 v[0:1], v[56:57], v[34:35], v[0:1] op_sel_hi:[0,1,1]
	s_waitcnt vmcnt(16)
	v_pk_fma_f32 v[4:5], v[58:59], v[30:31], v[4:5] op_sel_hi:[0,1,1]
	v_pk_fma_f32 v[0:1], v[58:59], v[38:39], v[0:1] op_sel_hi:[0,1,1]
	v_add_co_u32_e64 v14, s[4:5], s14, v6
	v_add_co_u32_e32 v12, vcc, 0xfffd0000, v6
	s_nop 0
	v_addc_co_u32_e64 v15, s[4:5], -1, v7, s[4:5]
	v_add_co_u32_e64 v16, s[4:5], s15, v6
	global_load_dword v44, v[6:7], off
	s_nop 0
	v_addc_co_u32_e64 v17, s[4:5], -1, v7, s[4:5]
	v_add_co_u32_e64 v18, s[4:5], s16, v6
	v_addc_co_u32_e32 v13, vcc, -1, v7, vcc
	s_nop 0
	v_addc_co_u32_e64 v19, s[4:5], -1, v7, s[4:5]
	v_add_co_u32_e64 v20, s[4:5], s13, v6
	s_nop 1
	v_addc_co_u32_e64 v21, s[4:5], 0, v7, s[4:5]
	v_add_co_u32_e64 v22, s[4:5], s17, v6
	s_nop 1
	v_addc_co_u32_e64 v23, s[4:5], 0, v7, s[4:5]
	v_add_co_u32_e64 v24, s[4:5], s18, v6
	s_nop 1
	v_addc_co_u32_e64 v25, s[4:5], 0, v7, s[4:5]
	global_load_dword v46, v[14:15], off
	global_load_dword v48, v[16:17], off
	global_load_dword v50, v[12:13], off
	global_load_dword v52, v[18:19], off
	global_load_dword v54, v[20:21], off
	global_load_dword v56, v[22:23], off
	global_load_dword v58, v[24:25], off
	v_lshl_add_u64 v[6:7], v[6:7], 0, s[10:11]
	ds_read_b128 v[12:15], v11 offset:32
	ds_read_b128 v[16:19], v11 offset:544
	ds_read_b128 v[20:23], v11 offset:1056
	ds_read_b128 v[24:27], v11 offset:1568
	ds_read_b128 v[28:31], v11 offset:48
	ds_read_b128 v[32:35], v11 offset:560
	ds_read_b128 v[36:39], v11 offset:1072
	ds_read_b128 v[40:43], v11 offset:1584
	s_waitcnt lgkmcnt(6)
	v_mov_b32_e32 v60, v16
	v_mov_b32_e32 v61, v12
	s_waitcnt lgkmcnt(4)
	v_mov_b32_e32 v62, v24
	v_mov_b32_e32 v63, v20
	v_mov_b32_e32 v12, v17
	v_mov_b32_e32 v20, v25
	v_mov_b32_e32 v16, v18
	v_mov_b32_e32 v17, v14
	v_mov_b32_e32 v14, v19
	v_mov_b32_e32 v18, v26
	v_mov_b32_e32 v19, v22
	v_mov_b32_e32 v22, v27
	s_waitcnt lgkmcnt(2)
	v_mov_b32_e32 v24, v32
	v_mov_b32_e32 v25, v28
	s_waitcnt lgkmcnt(0)
	v_mov_b32_e32 v26, v40
	v_mov_b32_e32 v27, v36
	v_mov_b32_e32 v28, v33
	v_mov_b32_e32 v36, v41
	v_mov_b32_e32 v32, v34
	v_mov_b32_e32 v33, v30
	v_mov_b32_e32 v30, v35
	v_mov_b32_e32 v34, v42
	v_mov_b32_e32 v35, v38
	v_mov_b32_e32 v38, v43
	s_waitcnt vmcnt(20)
	v_pk_fma_f32 v[4:5], v[70:71], v[60:61], v[4:5] op_sel_hi:[0,1,1]
	v_pk_fma_f32 v[0:1], v[70:71], v[62:63], v[0:1] op_sel_hi:[0,1,1]
	v_pk_fma_f32 v[4:5], v[66:67], v[12:13], v[4:5] op_sel_hi:[0,1,1]
	v_pk_fma_f32 v[0:1], v[66:67], v[20:21], v[0:1] op_sel_hi:[0,1,1]
	v_pk_fma_f32 v[4:5], v[68:69], v[16:17], v[4:5] op_sel_hi:[0,1,1]
	v_pk_fma_f32 v[0:1], v[68:69], v[18:19], v[0:1] op_sel_hi:[0,1,1]
	s_waitcnt vmcnt(19)
	v_pk_fma_f32 v[4:5], v[72:73], v[14:15], v[4:5] op_sel_hi:[0,1,1]
	v_pk_fma_f32 v[0:1], v[72:73], v[22:23], v[0:1] op_sel_hi:[0,1,1]
	v_pk_fma_f32 v[4:5], v[64:65], v[24:25], v[4:5] op_sel_hi:[0,1,1]
	v_pk_fma_f32 v[0:1], v[64:65], v[26:27], v[0:1] op_sel_hi:[0,1,1]
	s_waitcnt vmcnt(18)
	v_pk_fma_f32 v[4:5], v[74:75], v[28:29], v[4:5] op_sel_hi:[0,1,1]
	v_pk_fma_f32 v[0:1], v[74:75], v[36:37], v[0:1] op_sel_hi:[0,1,1]
	s_waitcnt vmcnt(17)
	v_pk_fma_f32 v[4:5], v[76:77], v[32:33], v[4:5] op_sel_hi:[0,1,1]
	v_pk_fma_f32 v[0:1], v[76:77], v[34:35], v[0:1] op_sel_hi:[0,1,1]
	s_waitcnt vmcnt(16)
	v_pk_fma_f32 v[4:5], v[78:79], v[30:31], v[4:5] op_sel_hi:[0,1,1]
	v_pk_fma_f32 v[0:1], v[78:79], v[38:39], v[0:1] op_sel_hi:[0,1,1]
	v_add_co_u32_e64 v14, s[4:5], s14, v6
	v_add_co_u32_e32 v12, vcc, 0xfffd0000, v6
	s_nop 0
	v_addc_co_u32_e64 v15, s[4:5], -1, v7, s[4:5]
	v_add_co_u32_e64 v16, s[4:5], s15, v6
	global_load_dword v64, v[6:7], off
	s_nop 0
	v_addc_co_u32_e64 v17, s[4:5], -1, v7, s[4:5]
	v_add_co_u32_e64 v18, s[4:5], s16, v6
	v_addc_co_u32_e32 v13, vcc, -1, v7, vcc
	s_nop 0
	v_addc_co_u32_e64 v19, s[4:5], -1, v7, s[4:5]
	v_add_co_u32_e64 v20, s[4:5], s13, v6
	s_nop 1
	v_addc_co_u32_e64 v21, s[4:5], 0, v7, s[4:5]
	v_add_co_u32_e64 v22, s[4:5], s17, v6
	s_nop 1
	v_addc_co_u32_e64 v23, s[4:5], 0, v7, s[4:5]
	v_add_co_u32_e64 v24, s[4:5], s18, v6
	s_nop 1
	v_addc_co_u32_e64 v25, s[4:5], 0, v7, s[4:5]
	global_load_dword v66, v[14:15], off
	global_load_dword v68, v[16:17], off
	global_load_dword v70, v[12:13], off
	global_load_dword v72, v[18:19], off
	global_load_dword v74, v[20:21], off
	global_load_dword v76, v[22:23], off
	global_load_dword v78, v[24:25], off
	v_lshl_add_u64 v[6:7], v[6:7], 0, s[10:11]
	ds_read_b128 v[12:15], v11 offset:64
	ds_read_b128 v[16:19], v11 offset:576
	ds_read_b128 v[20:23], v11 offset:1088
	ds_read_b128 v[24:27], v11 offset:1600
	ds_read_b128 v[28:31], v11 offset:80
	ds_read_b128 v[32:35], v11 offset:592
	ds_read_b128 v[36:39], v11 offset:1104
	ds_read_b128 v[40:43], v11 offset:1616
	s_waitcnt lgkmcnt(6)
	v_mov_b32_e32 v60, v16
	v_mov_b32_e32 v61, v12
	s_waitcnt lgkmcnt(4)
	v_mov_b32_e32 v62, v24
	v_mov_b32_e32 v63, v20
	v_mov_b32_e32 v12, v17
	v_mov_b32_e32 v20, v25
	v_mov_b32_e32 v16, v18
	v_mov_b32_e32 v17, v14
	v_mov_b32_e32 v14, v19
	v_mov_b32_e32 v18, v26
	v_mov_b32_e32 v19, v22
	v_mov_b32_e32 v22, v27
	s_waitcnt lgkmcnt(2)
	v_mov_b32_e32 v24, v32
	v_mov_b32_e32 v25, v28
	s_waitcnt lgkmcnt(0)
; DI void ada_partials(const P& p, LAS unsigned char* L) {
;     ...
;         float a0 = 0.f, a1 = 0.f, a2 = 0.f, a3 = 0.f;
; #pragma unroll 8
;         for (int k = 0; k < 128; ++k) { const float wv = w[(size_t)k * MODW]; a0 += condl[k] * wv; a1 += condl[128 + k] * wv; a2 += condl[256 + k] * wv; a3 += condl[384 + k] * wv; }
	v_mov_b32_e32 v26, v40
	v_mov_b32_e32 v27, v36
	v_mov_b32_e32 v28, v33
	v_mov_b32_e32 v36, v41
	v_mov_b32_e32 v32, v34
	v_mov_b32_e32 v33, v30
	v_mov_b32_e32 v30, v35
	v_mov_b32_e32 v34, v42
	v_mov_b32_e32 v35, v38
	v_mov_b32_e32 v38, v43
	s_waitcnt vmcnt(20)
	v_pk_fma_f32 v[4:5], v[86:87], v[60:61], v[4:5] op_sel_hi:[0,1,1]
	v_pk_fma_f32 v[0:1], v[86:87], v[62:63], v[0:1] op_sel_hi:[0,1,1]
	v_pk_fma_f32 v[4:5], v[82:83], v[12:13], v[4:5] op_sel_hi:[0,1,1]
	v_pk_fma_f32 v[0:1], v[82:83], v[20:21], v[0:1] op_sel_hi:[0,1,1]
	v_pk_fma_f32 v[4:5], v[84:85], v[16:17], v[4:5] op_sel_hi:[0,1,1]
	v_pk_fma_f32 v[0:1], v[84:85], v[18:19], v[0:1] op_sel_hi:[0,1,1]
	s_waitcnt vmcnt(19)
	v_pk_fma_f32 v[4:5], v[88:89], v[14:15], v[4:5] op_sel_hi:[0,1,1]
	v_pk_fma_f32 v[0:1], v[88:89], v[22:23], v[0:1] op_sel_hi:[0,1,1]
	v_pk_fma_f32 v[4:5], v[80:81], v[24:25], v[4:5] op_sel_hi:[0,1,1]
	v_pk_fma_f32 v[0:1], v[80:81], v[26:27], v[0:1] op_sel_hi:[0,1,1]
	s_waitcnt vmcnt(18)
	v_pk_fma_f32 v[4:5], v[90:91], v[28:29], v[4:5] op_sel_hi:[0,1,1]
	v_pk_fma_f32 v[0:1], v[90:91], v[36:37], v[0:1] op_sel_hi:[0,1,1]
	s_waitcnt vmcnt(17)
	v_pk_fma_f32 v[4:5], v[92:93], v[32:33], v[4:5] op_sel_hi:[0,1,1]
	v_pk_fma_f32 v[0:1], v[92:93], v[34:35], v[0:1] op_sel_hi:[0,1,1]
	s_waitcnt vmcnt(16)
	v_pk_fma_f32 v[4:5], v[94:95], v[30:31], v[4:5] op_sel_hi:[0,1,1]
	v_pk_fma_f32 v[0:1], v[94:95], v[38:39], v[0:1] op_sel_hi:[0,1,1]
	v_add_co_u32_e64 v14, s[4:5], s14, v6
	v_add_co_u32_e32 v12, vcc, 0xfffd0000, v6
	s_nop 0
	v_addc_co_u32_e64 v15, s[4:5], -1, v7, s[4:5]
	v_add_co_u32_e64 v16, s[4:5], s15, v6
	global_load_dword v80, v[6:7], off
	s_nop 0
	v_addc_co_u32_e64 v17, s[4:5], -1, v7, s[4:5]
	v_add_co_u32_e64 v18, s[4:5], s16, v6
	v_addc_co_u32_e32 v13, vcc, -1, v7, vcc
	s_nop 0
	v_addc_co_u32_e64 v19, s[4:5], -1, v7, s[4:5]
	v_add_co_u32_e64 v20, s[4:5], s13, v6
	s_nop 1
	v_addc_co_u32_e64 v21, s[4:5], 0, v7, s[4:5]
	v_add_co_u32_e64 v22, s[4:5], s17, v6
	s_nop 1
	v_addc_co_u32_e64 v23, s[4:5], 0, v7, s[4:5]
	v_add_co_u32_e64 v24, s[4:5], s18, v6
	s_nop 1
	v_addc_co_u32_e64 v25, s[4:5], 0, v7, s[4:5]
	global_load_dword v82, v[14:15], off
	global_load_dword v84, v[16:17], off
	global_load_dword v86, v[12:13], off
	global_load_dword v88, v[18:19], off
	global_load_dword v90, v[20:21], off
	global_load_dword v92, v[22:23], off
	global_load_dword v94, v[24:25], off
	v_lshl_add_u64 v[6:7], v[6:7], 0, s[10:11]
	ds_read_b128 v[12:15], v11 offset:96
	ds_read_b128 v[16:19], v11 offset:608
	ds_read_b128 v[20:23], v11 offset:1120
	ds_read_b128 v[24:27], v11 offset:1632
	ds_read_b128 v[28:31], v11 offset:112
	ds_read_b128 v[32:35], v11 offset:624
	ds_read_b128 v[36:39], v11 offset:1136
	ds_read_b128 v[40:43], v11 offset:1648
	s_waitcnt lgkmcnt(6)
	v_mov_b32_e32 v60, v16
	v_mov_b32_e32 v61, v12
	s_waitcnt lgkmcnt(4)
	v_mov_b32_e32 v62, v24
	v_mov_b32_e32 v63, v20
	v_mov_b32_e32 v12, v17
	v_mov_b32_e32 v20, v25
	v_mov_b32_e32 v16, v18
	v_mov_b32_e32 v17, v14
	v_mov_b32_e32 v14, v19
	v_mov_b32_e32 v18, v26
	v_mov_b32_e32 v19, v22
	v_mov_b32_e32 v22, v27
	s_waitcnt lgkmcnt(2)
	v_mov_b32_e32 v24, v32
	v_mov_b32_e32 v25, v28
	s_waitcnt lgkmcnt(0)
	v_mov_b32_e32 v26, v40
	v_mov_b32_e32 v27, v36
	v_mov_b32_e32 v28, v33
	v_mov_b32_e32 v36, v41
	v_mov_b32_e32 v32, v34
	v_mov_b32_e32 v33, v30
	v_mov_b32_e32 v30, v35
	v_mov_b32_e32 v34, v42
	v_mov_b32_e32 v35, v38
	v_mov_b32_e32 v38, v43
	s_waitcnt vmcnt(20)
	v_pk_fma_f32 v[4:5], v[50:51], v[60:61], v[4:5] op_sel_hi:[0,1,1]
	v_pk_fma_f32 v[0:1], v[50:51], v[62:63], v[0:1] op_sel_hi:[0,1,1]
	v_pk_fma_f32 v[4:5], v[46:47], v[12:13], v[4:5] op_sel_hi:[0,1,1]
	v_pk_fma_f32 v[0:1], v[46:47], v[20:21], v[0:1] op_sel_hi:[0,1,1]
	v_pk_fma_f32 v[4:5], v[48:49], v[16:17], v[4:5] op_sel_hi:[0,1,1]
	v_pk_fma_f32 v[0:1], v[48:49], v[18:19], v[0:1] op_sel_hi:[0,1,1]
	s_waitcnt vmcnt(19)
	v_pk_fma_f32 v[4:5], v[52:53], v[14:15], v[4:5] op_sel_hi:[0,1,1]
	v_pk_fma_f32 v[0:1], v[52:53], v[22:23], v[0:1] op_sel_hi:[0,1,1]
	v_pk_fma_f32 v[4:5], v[44:45], v[24:25], v[4:5] op_sel_hi:[0,1,1]
	v_pk_fma_f32 v[0:1], v[44:45], v[26:27], v[0:1] op_sel_hi:[0,1,1]
	s_waitcnt vmcnt(18)
	v_pk_fma_f32 v[4:5], v[54:55], v[28:29], v[4:5] op_sel_hi:[0,1,1]
	v_pk_fma_f32 v[0:1], v[54:55], v[36:37], v[0:1] op_sel_hi:[0,1,1]
	s_waitcnt vmcnt(17)
	v_pk_fma_f32 v[4:5], v[56:57], v[32:33], v[4:5] op_sel_hi:[0,1,1]
	v_pk_fma_f32 v[0:1], v[56:57], v[34:35], v[0:1] op_sel_hi:[0,1,1]
	s_waitcnt vmcnt(16)
	v_pk_fma_f32 v[4:5], v[58:59], v[30:31], v[4:5] op_sel_hi:[0,1,1]
	v_pk_fma_f32 v[0:1], v[58:59], v[38:39], v[0:1] op_sel_hi:[0,1,1]
	v_add_co_u32_e64 v14, s[4:5], s14, v6
	v_add_co_u32_e32 v12, vcc, 0xfffd0000, v6
	s_nop 0
	v_addc_co_u32_e64 v15, s[4:5], -1, v7, s[4:5]
	v_add_co_u32_e64 v16, s[4:5], s15, v6
	global_load_dword v44, v[6:7], off
	s_nop 0
	v_addc_co_u32_e64 v17, s[4:5], -1, v7, s[4:5]
	v_add_co_u32_e64 v18, s[4:5], s16, v6
	v_addc_co_u32_e32 v13, vcc, -1, v7, vcc
	s_nop 0
	v_addc_co_u32_e64 v19, s[4:5], -1, v7, s[4:5]
	v_add_co_u32_e64 v20, s[4:5], s13, v6
	s_nop 1
	v_addc_co_u32_e64 v21, s[4:5], 0, v7, s[4:5]
	v_add_co_u32_e64 v22, s[4:5], s17, v6
	s_nop 1
	v_addc_co_u32_e64 v23, s[4:5], 0, v7, s[4:5]
	v_add_co_u32_e64 v24, s[4:5], s18, v6
	s_nop 1
	v_addc_co_u32_e64 v25, s[4:5], 0, v7, s[4:5]
	global_load_dword v46, v[14:15], off
	global_load_dword v48, v[16:17], off
	global_load_dword v50, v[12:13], off
	global_load_dword v52, v[18:19], off
	global_load_dword v54, v[20:21], off
	global_load_dword v56, v[22:23], off
	global_load_dword v58, v[24:25], off
	v_lshl_add_u64 v[6:7], v[6:7], 0, s[10:11]
	ds_read_b128 v[12:15], v11 offset:128
	ds_read_b128 v[16:19], v11 offset:640
	ds_read_b128 v[20:23], v11 offset:1152
	ds_read_b128 v[24:27], v11 offset:1664
	ds_read_b128 v[28:31], v11 offset:144
	ds_read_b128 v[32:35], v11 offset:656
	ds_read_b128 v[36:39], v11 offset:1168
	ds_read_b128 v[40:43], v11 offset:1680
	s_waitcnt lgkmcnt(6)
; DI void ada_partials(const P& p, LAS unsigned char* L) {
;     ...
;         float a0 = 0.f, a1 = 0.f, a2 = 0.f, a3 = 0.f;
; #pragma unroll 8
;         for (int k = 0; k < 128; ++k) { const float wv = w[(size_t)k * MODW]; a0 += condl[k] * wv; a1 += condl[128 + k] * wv; a2 += condl[256 + k] * wv; a3 += condl[384 + k] * wv; }
	v_mov_b32_e32 v60, v16
	v_mov_b32_e32 v61, v12
	s_waitcnt lgkmcnt(4)
	v_mov_b32_e32 v62, v24
	v_mov_b32_e32 v63, v20
	v_mov_b32_e32 v12, v17
	v_mov_b32_e32 v20, v25
	v_mov_b32_e32 v16, v18
	v_mov_b32_e32 v17, v14
	v_mov_b32_e32 v14, v19
	v_mov_b32_e32 v18, v26
	v_mov_b32_e32 v19, v22
	v_mov_b32_e32 v22, v27
	s_waitcnt lgkmcnt(2)
	v_mov_b32_e32 v24, v32
	v_mov_b32_e32 v25, v28
	s_waitcnt lgkmcnt(0)
	v_mov_b32_e32 v26, v40
	v_mov_b32_e32 v27, v36
	v_mov_b32_e32 v28, v33
	v_mov_b32_e32 v36, v41
	v_mov_b32_e32 v32, v34
	v_mov_b32_e32 v33, v30
	v_mov_b32_e32 v30, v35
	v_mov_b32_e32 v34, v42
	v_mov_b32_e32 v35, v38
	v_mov_b32_e32 v38, v43
	s_waitcnt vmcnt(20)
	v_pk_fma_f32 v[4:5], v[70:71], v[60:61], v[4:5] op_sel_hi:[0,1,1]
	v_pk_fma_f32 v[0:1], v[70:71], v[62:63], v[0:1] op_sel_hi:[0,1,1]
	v_pk_fma_f32 v[4:5], v[66:67], v[12:13], v[4:5] op_sel_hi:[0,1,1]
	v_pk_fma_f32 v[0:1], v[66:67], v[20:21], v[0:1] op_sel_hi:[0,1,1]
	v_pk_fma_f32 v[4:5], v[68:69], v[16:17], v[4:5] op_sel_hi:[0,1,1]
	v_pk_fma_f32 v[0:1], v[68:69], v[18:19], v[0:1] op_sel_hi:[0,1,1]
	s_waitcnt vmcnt(19)
	v_pk_fma_f32 v[4:5], v[72:73], v[14:15], v[4:5] op_sel_hi:[0,1,1]
	v_pk_fma_f32 v[0:1], v[72:73], v[22:23], v[0:1] op_sel_hi:[0,1,1]
	v_pk_fma_f32 v[4:5], v[64:65], v[24:25], v[4:5] op_sel_hi:[0,1,1]
	v_pk_fma_f32 v[0:1], v[64:65], v[26:27], v[0:1] op_sel_hi:[0,1,1]
	s_waitcnt vmcnt(18)
	v_pk_fma_f32 v[4:5], v[74:75], v[28:29], v[4:5] op_sel_hi:[0,1,1]
	v_pk_fma_f32 v[0:1], v[74:75], v[36:37], v[0:1] op_sel_hi:[0,1,1]
	s_waitcnt vmcnt(17)
	v_pk_fma_f32 v[4:5], v[76:77], v[32:33], v[4:5] op_sel_hi:[0,1,1]
	v_pk_fma_f32 v[0:1], v[76:77], v[34:35], v[0:1] op_sel_hi:[0,1,1]
	s_waitcnt vmcnt(16)
	v_pk_fma_f32 v[4:5], v[78:79], v[30:31], v[4:5] op_sel_hi:[0,1,1]
	v_pk_fma_f32 v[0:1], v[78:79], v[38:39], v[0:1] op_sel_hi:[0,1,1]
	v_add_co_u32_e64 v14, s[4:5], s14, v6
	v_add_co_u32_e32 v12, vcc, 0xfffd0000, v6
	s_nop 0
	v_addc_co_u32_e64 v15, s[4:5], -1, v7, s[4:5]
	v_add_co_u32_e64 v16, s[4:5], s15, v6
	global_load_dword v64, v[6:7], off
	s_nop 0
	v_addc_co_u32_e64 v17, s[4:5], -1, v7, s[4:5]
	v_add_co_u32_e64 v18, s[4:5], s16, v6
	v_addc_co_u32_e32 v13, vcc, -1, v7, vcc
	s_nop 0
	v_addc_co_u32_e64 v19, s[4:5], -1, v7, s[4:5]
	v_add_co_u32_e64 v20, s[4:5], s13, v6
	s_nop 1
	v_addc_co_u32_e64 v21, s[4:5], 0, v7, s[4:5]
	v_add_co_u32_e64 v22, s[4:5], s17, v6
	s_nop 1
	v_addc_co_u32_e64 v23, s[4:5], 0, v7, s[4:5]
	v_add_co_u32_e64 v24, s[4:5], s18, v6
	s_nop 1
	v_addc_co_u32_e64 v25, s[4:5], 0, v7, s[4:5]
	global_load_dword v66, v[14:15], off
	global_load_dword v68, v[16:17], off
	global_load_dword v70, v[12:13], off
	global_load_dword v72, v[18:19], off
	global_load_dword v74, v[20:21], off
	global_load_dword v76, v[22:23], off
	global_load_dword v78, v[24:25], off
	v_lshl_add_u64 v[6:7], v[6:7], 0, s[10:11]
	ds_read_b128 v[12:15], v11 offset:160
	ds_read_b128 v[16:19], v11 offset:672
	ds_read_b128 v[20:23], v11 offset:1184
	ds_read_b128 v[24:27], v11 offset:1696
	ds_read_b128 v[28:31], v11 offset:176
	ds_read_b128 v[32:35], v11 offset:688
	ds_read_b128 v[36:39], v11 offset:1200
	ds_read_b128 v[40:43], v11 offset:1712
	s_waitcnt lgkmcnt(6)
	v_mov_b32_e32 v60, v16
	v_mov_b32_e32 v61, v12
	s_waitcnt lgkmcnt(4)
	v_mov_b32_e32 v62, v24
	v_mov_b32_e32 v63, v20
	v_mov_b32_e32 v12, v17
	v_mov_b32_e32 v20, v25
	v_mov_b32_e32 v16, v18
	v_mov_b32_e32 v17, v14
	v_mov_b32_e32 v14, v19
	v_mov_b32_e32 v18, v26
	v_mov_b32_e32 v19, v22
	v_mov_b32_e32 v22, v27
	s_waitcnt lgkmcnt(2)
	v_mov_b32_e32 v24, v32
	v_mov_b32_e32 v25, v28
	s_waitcnt lgkmcnt(0)
	v_mov_b32_e32 v26, v40
	v_mov_b32_e32 v27, v36
	v_mov_b32_e32 v28, v33
	v_mov_b32_e32 v36, v41
	v_mov_b32_e32 v32, v34
	v_mov_b32_e32 v33, v30
	v_mov_b32_e32 v30, v35
	v_mov_b32_e32 v34, v42
	v_mov_b32_e32 v35, v38
	v_mov_b32_e32 v38, v43
	s_waitcnt vmcnt(20)
	v_pk_fma_f32 v[4:5], v[86:87], v[60:61], v[4:5] op_sel_hi:[0,1,1]
	v_pk_fma_f32 v[0:1], v[86:87], v[62:63], v[0:1] op_sel_hi:[0,1,1]
	v_pk_fma_f32 v[4:5], v[82:83], v[12:13], v[4:5] op_sel_hi:[0,1,1]
	v_pk_fma_f32 v[0:1], v[82:83], v[20:21], v[0:1] op_sel_hi:[0,1,1]
	v_pk_fma_f32 v[4:5], v[84:85], v[16:17], v[4:5] op_sel_hi:[0,1,1]
	v_pk_fma_f32 v[0:1], v[84:85], v[18:19], v[0:1] op_sel_hi:[0,1,1]
	s_waitcnt vmcnt(19)
	v_pk_fma_f32 v[4:5], v[88:89], v[14:15], v[4:5] op_sel_hi:[0,1,1]
	v_pk_fma_f32 v[0:1], v[88:89], v[22:23], v[0:1] op_sel_hi:[0,1,1]
	v_pk_fma_f32 v[4:5], v[80:81], v[24:25], v[4:5] op_sel_hi:[0,1,1]
	v_pk_fma_f32 v[0:1], v[80:81], v[26:27], v[0:1] op_sel_hi:[0,1,1]
	s_waitcnt vmcnt(18)
	v_pk_fma_f32 v[4:5], v[90:91], v[28:29], v[4:5] op_sel_hi:[0,1,1]
	v_pk_fma_f32 v[0:1], v[90:91], v[36:37], v[0:1] op_sel_hi:[0,1,1]
	s_waitcnt vmcnt(17)
	v_pk_fma_f32 v[4:5], v[92:93], v[32:33], v[4:5] op_sel_hi:[0,1,1]
	v_pk_fma_f32 v[0:1], v[92:93], v[34:35], v[0:1] op_sel_hi:[0,1,1]
	s_waitcnt vmcnt(16)
	v_pk_fma_f32 v[4:5], v[94:95], v[30:31], v[4:5] op_sel_hi:[0,1,1]
	v_pk_fma_f32 v[0:1], v[94:95], v[38:39], v[0:1] op_sel_hi:[0,1,1]
	v_add_co_u32_e64 v14, s[4:5], s14, v6
	v_add_co_u32_e32 v12, vcc, 0xfffd0000, v6
	s_nop 0
	v_addc_co_u32_e64 v15, s[4:5], -1, v7, s[4:5]
	v_add_co_u32_e64 v16, s[4:5], s15, v6
	global_load_dword v80, v[6:7], off
	s_nop 0
	v_addc_co_u32_e64 v17, s[4:5], -1, v7, s[4:5]
	v_add_co_u32_e64 v18, s[4:5], s16, v6
	v_addc_co_u32_e32 v13, vcc, -1, v7, vcc
	s_nop 0
	v_addc_co_u32_e64 v19, s[4:5], -1, v7, s[4:5]
	v_add_co_u32_e64 v20, s[4:5], s13, v6
	s_nop 1
	v_addc_co_u32_e64 v21, s[4:5], 0, v7, s[4:5]
	v_add_co_u32_e64 v22, s[4:5], s17, v6
	s_nop 1
	v_addc_co_u32_e64 v23, s[4:5], 0, v7, s[4:5]
	v_add_co_u32_e64 v24, s[4:5], s18, v6
	s_nop 1
	v_addc_co_u32_e64 v25, s[4:5], 0, v7, s[4:5]
	global_load_dword v82, v[14:15], off
	global_load_dword v84, v[16:17], off
	global_load_dword v86, v[12:13], off
	global_load_dword v88, v[18:19], off
	global_load_dword v90, v[20:21], off
	global_load_dword v92, v[22:23], off
	global_load_dword v94, v[24:25], off
	v_lshl_add_u64 v[6:7], v[6:7], 0, s[10:11]
	ds_read_b128 v[12:15], v11 offset:192
	ds_read_b128 v[16:19], v11 offset:704
	ds_read_b128 v[20:23], v11 offset:1216
	ds_read_b128 v[24:27], v11 offset:1728
	ds_read_b128 v[28:31], v11 offset:208
	ds_read_b128 v[32:35], v11 offset:720
	ds_read_b128 v[36:39], v11 offset:1232
	ds_read_b128 v[40:43], v11 offset:1744
	s_waitcnt lgkmcnt(6)
; DI void ada_partials(const P& p, LAS unsigned char* L) {
;     ...
;         float a0 = 0.f, a1 = 0.f, a2 = 0.f, a3 = 0.f;
; #pragma unroll 8
;         for (int k = 0; k < 128; ++k) { const float wv = w[(size_t)k * MODW]; a0 += condl[k] * wv; a1 += condl[128 + k] * wv; a2 += condl[256 + k] * wv; a3 += condl[384 + k] * wv; }
	v_mov_b32_e32 v60, v16
	v_mov_b32_e32 v61, v12
	s_waitcnt lgkmcnt(4)
	v_mov_b32_e32 v62, v24
	v_mov_b32_e32 v63, v20
	v_mov_b32_e32 v12, v17
	v_mov_b32_e32 v20, v25
	v_mov_b32_e32 v16, v18
	v_mov_b32_e32 v17, v14
	v_mov_b32_e32 v14, v19
	v_mov_b32_e32 v18, v26
	v_mov_b32_e32 v19, v22
	v_mov_b32_e32 v22, v27
	s_waitcnt lgkmcnt(2)
	v_mov_b32_e32 v24, v32
	v_mov_b32_e32 v25, v28
	s_waitcnt lgkmcnt(0)
	v_mov_b32_e32 v26, v40
	v_mov_b32_e32 v27, v36
	v_mov_b32_e32 v28, v33
	v_mov_b32_e32 v36, v41
	v_mov_b32_e32 v32, v34
	v_mov_b32_e32 v33, v30
	v_mov_b32_e32 v30, v35
	v_mov_b32_e32 v34, v42
	v_mov_b32_e32 v35, v38
	v_mov_b32_e32 v38, v43
	s_waitcnt vmcnt(20)
	v_pk_fma_f32 v[4:5], v[50:51], v[60:61], v[4:5] op_sel_hi:[0,1,1]
	v_pk_fma_f32 v[0:1], v[50:51], v[62:63], v[0:1] op_sel_hi:[0,1,1]
	v_pk_fma_f32 v[4:5], v[46:47], v[12:13], v[4:5] op_sel_hi:[0,1,1]
	v_pk_fma_f32 v[0:1], v[46:47], v[20:21], v[0:1] op_sel_hi:[0,1,1]
	v_pk_fma_f32 v[4:5], v[48:49], v[16:17], v[4:5] op_sel_hi:[0,1,1]
	v_pk_fma_f32 v[0:1], v[48:49], v[18:19], v[0:1] op_sel_hi:[0,1,1]
	s_waitcnt vmcnt(19)
	v_pk_fma_f32 v[4:5], v[52:53], v[14:15], v[4:5] op_sel_hi:[0,1,1]
	v_pk_fma_f32 v[0:1], v[52:53], v[22:23], v[0:1] op_sel_hi:[0,1,1]
	v_pk_fma_f32 v[4:5], v[44:45], v[24:25], v[4:5] op_sel_hi:[0,1,1]
	v_pk_fma_f32 v[0:1], v[44:45], v[26:27], v[0:1] op_sel_hi:[0,1,1]
	s_waitcnt vmcnt(18)
	v_pk_fma_f32 v[4:5], v[54:55], v[28:29], v[4:5] op_sel_hi:[0,1,1]
	v_pk_fma_f32 v[0:1], v[54:55], v[36:37], v[0:1] op_sel_hi:[0,1,1]
	s_waitcnt vmcnt(17)
	v_pk_fma_f32 v[4:5], v[56:57], v[32:33], v[4:5] op_sel_hi:[0,1,1]
	v_pk_fma_f32 v[0:1], v[56:57], v[34:35], v[0:1] op_sel_hi:[0,1,1]
	s_waitcnt vmcnt(16)
	v_pk_fma_f32 v[4:5], v[58:59], v[30:31], v[4:5] op_sel_hi:[0,1,1]
	v_pk_fma_f32 v[0:1], v[58:59], v[38:39], v[0:1] op_sel_hi:[0,1,1]
	v_add_co_u32_e64 v14, s[4:5], s14, v6
	v_add_co_u32_e32 v12, vcc, 0xfffd0000, v6
	s_nop 0
	v_addc_co_u32_e64 v15, s[4:5], -1, v7, s[4:5]
	v_add_co_u32_e64 v16, s[4:5], s15, v6
	global_load_dword v44, v[6:7], off
	s_nop 0
	v_addc_co_u32_e64 v17, s[4:5], -1, v7, s[4:5]
	v_add_co_u32_e64 v18, s[4:5], s16, v6
	v_addc_co_u32_e32 v13, vcc, -1, v7, vcc
	s_nop 0
	v_addc_co_u32_e64 v19, s[4:5], -1, v7, s[4:5]
	v_add_co_u32_e64 v20, s[4:5], s13, v6
	s_nop 1
	v_addc_co_u32_e64 v21, s[4:5], 0, v7, s[4:5]
	v_add_co_u32_e64 v22, s[4:5], s17, v6
	s_nop 1
	v_addc_co_u32_e64 v23, s[4:5], 0, v7, s[4:5]
	v_add_co_u32_e64 v24, s[4:5], s18, v6
	s_nop 1
	v_addc_co_u32_e64 v25, s[4:5], 0, v7, s[4:5]
	global_load_dword v46, v[14:15], off
	global_load_dword v48, v[16:17], off
	global_load_dword v50, v[12:13], off
	global_load_dword v52, v[18:19], off
	global_load_dword v54, v[20:21], off
	global_load_dword v56, v[22:23], off
	global_load_dword v58, v[24:25], off
	v_lshl_add_u64 v[6:7], v[6:7], 0, s[10:11]
	ds_read_b128 v[12:15], v11 offset:224
	ds_read_b128 v[16:19], v11 offset:736
	ds_read_b128 v[20:23], v11 offset:1248
	ds_read_b128 v[24:27], v11 offset:1760
	ds_read_b128 v[28:31], v11 offset:240
	ds_read_b128 v[32:35], v11 offset:752
	ds_read_b128 v[36:39], v11 offset:1264
	ds_read_b128 v[40:43], v11 offset:1776
	s_waitcnt lgkmcnt(6)
	v_mov_b32_e32 v60, v16
	v_mov_b32_e32 v61, v12
	s_waitcnt lgkmcnt(4)
	v_mov_b32_e32 v62, v24
	v_mov_b32_e32 v63, v20
	v_mov_b32_e32 v12, v17
	v_mov_b32_e32 v20, v25
	v_mov_b32_e32 v16, v18
	v_mov_b32_e32 v17, v14
	v_mov_b32_e32 v14, v19
	v_mov_b32_e32 v18, v26
	v_mov_b32_e32 v19, v22
	v_mov_b32_e32 v22, v27
	s_waitcnt lgkmcnt(2)
	v_mov_b32_e32 v24, v32
	v_mov_b32_e32 v25, v28
	s_waitcnt lgkmcnt(0)
	v_mov_b32_e32 v26, v40
	v_mov_b32_e32 v27, v36
	v_mov_b32_e32 v28, v33
	v_mov_b32_e32 v36, v41
	v_mov_b32_e32 v32, v34
	v_mov_b32_e32 v33, v30
	v_mov_b32_e32 v30, v35
	v_mov_b32_e32 v34, v42
	v_mov_b32_e32 v35, v38
	v_mov_b32_e32 v38, v43
	s_waitcnt vmcnt(20)
	v_pk_fma_f32 v[4:5], v[70:71], v[60:61], v[4:5] op_sel_hi:[0,1,1]
	v_pk_fma_f32 v[0:1], v[70:71], v[62:63], v[0:1] op_sel_hi:[0,1,1]
	v_pk_fma_f32 v[4:5], v[66:67], v[12:13], v[4:5] op_sel_hi:[0,1,1]
	v_pk_fma_f32 v[0:1], v[66:67], v[20:21], v[0:1] op_sel_hi:[0,1,1]
	v_pk_fma_f32 v[4:5], v[68:69], v[16:17], v[4:5] op_sel_hi:[0,1,1]
	v_pk_fma_f32 v[0:1], v[68:69], v[18:19], v[0:1] op_sel_hi:[0,1,1]
	s_waitcnt vmcnt(19)
	v_pk_fma_f32 v[4:5], v[72:73], v[14:15], v[4:5] op_sel_hi:[0,1,1]
	v_pk_fma_f32 v[0:1], v[72:73], v[22:23], v[0:1] op_sel_hi:[0,1,1]
	v_pk_fma_f32 v[4:5], v[64:65], v[24:25], v[4:5] op_sel_hi:[0,1,1]
	v_pk_fma_f32 v[0:1], v[64:65], v[26:27], v[0:1] op_sel_hi:[0,1,1]
	s_waitcnt vmcnt(18)
	v_pk_fma_f32 v[4:5], v[74:75], v[28:29], v[4:5] op_sel_hi:[0,1,1]
	v_pk_fma_f32 v[0:1], v[74:75], v[36:37], v[0:1] op_sel_hi:[0,1,1]
	s_waitcnt vmcnt(17)
	v_pk_fma_f32 v[4:5], v[76:77], v[32:33], v[4:5] op_sel_hi:[0,1,1]
	v_pk_fma_f32 v[0:1], v[76:77], v[34:35], v[0:1] op_sel_hi:[0,1,1]
	s_waitcnt vmcnt(16)
	v_pk_fma_f32 v[4:5], v[78:79], v[30:31], v[4:5] op_sel_hi:[0,1,1]
	v_pk_fma_f32 v[0:1], v[78:79], v[38:39], v[0:1] op_sel_hi:[0,1,1]
	v_add_co_u32_e64 v14, s[4:5], s14, v6
	v_add_co_u32_e32 v12, vcc, 0xfffd0000, v6
	s_nop 0
	v_addc_co_u32_e64 v15, s[4:5], -1, v7, s[4:5]
	v_add_co_u32_e64 v16, s[4:5], s15, v6
	global_load_dword v64, v[6:7], off
	s_nop 0
	v_addc_co_u32_e64 v17, s[4:5], -1, v7, s[4:5]
	v_add_co_u32_e64 v18, s[4:5], s16, v6
	v_addc_co_u32_e32 v13, vcc, -1, v7, vcc
	s_nop 0
	v_addc_co_u32_e64 v19, s[4:5], -1, v7, s[4:5]
	v_add_co_u32_e64 v20, s[4:5], s13, v6
	s_nop 1
	v_addc_co_u32_e64 v21, s[4:5], 0, v7, s[4:5]
	v_add_co_u32_e64 v22, s[4:5], s17, v6
	s_nop 1
	v_addc_co_u32_e64 v23, s[4:5], 0, v7, s[4:5]
	v_add_co_u32_e64 v24, s[4:5], s18, v6
	s_nop 1
	v_addc_co_u32_e64 v25, s[4:5], 0, v7, s[4:5]
	global_load_dword v66, v[14:15], off
	global_load_dword v68, v[16:17], off
	global_load_dword v70, v[12:13], off
	global_load_dword v72, v[18:19], off
	global_load_dword v74, v[20:21], off
	global_load_dword v76, v[22:23], off
	global_load_dword v78, v[24:25], off
	v_lshl_add_u64 v[6:7], v[6:7], 0, s[10:11]
	ds_read_b128 v[12:15], v11 offset:256
	ds_read_b128 v[16:19], v11 offset:768
	ds_read_b128 v[20:23], v11 offset:1280
	ds_read_b128 v[24:27], v11 offset:1792
	ds_read_b128 v[28:31], v11 offset:272
	ds_read_b128 v[32:35], v11 offset:784
	ds_read_b128 v[36:39], v11 offset:1296
	ds_read_b128 v[40:43], v11 offset:1808
	s_waitcnt lgkmcnt(6)
; DI void ada_partials(const P& p, LAS unsigned char* L) {
;     ...
;         float a0 = 0.f, a1 = 0.f, a2 = 0.f, a3 = 0.f;
; #pragma unroll 8
;         for (int k = 0; k < 128; ++k) { const float wv = w[(size_t)k * MODW]; a0 += condl[k] * wv; a1 += condl[128 + k] * wv; a2 += condl[256 + k] * wv; a3 += condl[384 + k] * wv; }
	v_mov_b32_e32 v60, v16
	v_mov_b32_e32 v61, v12
	s_waitcnt lgkmcnt(4)
	v_mov_b32_e32 v62, v24
	v_mov_b32_e32 v63, v20
	v_mov_b32_e32 v12, v17
	v_mov_b32_e32 v20, v25
	v_mov_b32_e32 v16, v18
	v_mov_b32_e32 v17, v14
	v_mov_b32_e32 v14, v19
	v_mov_b32_e32 v18, v26
	v_mov_b32_e32 v19, v22
	v_mov_b32_e32 v22, v27
	s_waitcnt lgkmcnt(2)
	v_mov_b32_e32 v24, v32
	v_mov_b32_e32 v25, v28
	s_waitcnt lgkmcnt(0)
	v_mov_b32_e32 v26, v40
	v_mov_b32_e32 v27, v36
	v_mov_b32_e32 v28, v33
	v_mov_b32_e32 v36, v41
	v_mov_b32_e32 v32, v34
	v_mov_b32_e32 v33, v30
	v_mov_b32_e32 v30, v35
	v_mov_b32_e32 v34, v42
	v_mov_b32_e32 v35, v38
	v_mov_b32_e32 v38, v43
	s_waitcnt vmcnt(20)
	v_pk_fma_f32 v[4:5], v[86:87], v[60:61], v[4:5] op_sel_hi:[0,1,1]
	v_pk_fma_f32 v[0:1], v[86:87], v[62:63], v[0:1] op_sel_hi:[0,1,1]
	v_pk_fma_f32 v[4:5], v[82:83], v[12:13], v[4:5] op_sel_hi:[0,1,1]
	v_pk_fma_f32 v[0:1], v[82:83], v[20:21], v[0:1] op_sel_hi:[0,1,1]
	v_pk_fma_f32 v[4:5], v[84:85], v[16:17], v[4:5] op_sel_hi:[0,1,1]
	v_pk_fma_f32 v[0:1], v[84:85], v[18:19], v[0:1] op_sel_hi:[0,1,1]
	s_waitcnt vmcnt(19)
	v_pk_fma_f32 v[4:5], v[88:89], v[14:15], v[4:5] op_sel_hi:[0,1,1]
	v_pk_fma_f32 v[0:1], v[88:89], v[22:23], v[0:1] op_sel_hi:[0,1,1]
	v_pk_fma_f32 v[4:5], v[80:81], v[24:25], v[4:5] op_sel_hi:[0,1,1]
	v_pk_fma_f32 v[0:1], v[80:81], v[26:27], v[0:1] op_sel_hi:[0,1,1]
	s_waitcnt vmcnt(18)
	v_pk_fma_f32 v[4:5], v[90:91], v[28:29], v[4:5] op_sel_hi:[0,1,1]
	v_pk_fma_f32 v[0:1], v[90:91], v[36:37], v[0:1] op_sel_hi:[0,1,1]
	s_waitcnt vmcnt(17)
	v_pk_fma_f32 v[4:5], v[92:93], v[32:33], v[4:5] op_sel_hi:[0,1,1]
	v_pk_fma_f32 v[0:1], v[92:93], v[34:35], v[0:1] op_sel_hi:[0,1,1]
	s_waitcnt vmcnt(16)
	v_pk_fma_f32 v[4:5], v[94:95], v[30:31], v[4:5] op_sel_hi:[0,1,1]
	v_pk_fma_f32 v[0:1], v[94:95], v[38:39], v[0:1] op_sel_hi:[0,1,1]
	v_add_co_u32_e64 v14, s[4:5], s14, v6
	v_add_co_u32_e32 v12, vcc, 0xfffd0000, v6
	s_nop 0
	v_addc_co_u32_e64 v15, s[4:5], -1, v7, s[4:5]
	v_add_co_u32_e64 v16, s[4:5], s15, v6
	global_load_dword v80, v[6:7], off
	s_nop 0
	v_addc_co_u32_e64 v17, s[4:5], -1, v7, s[4:5]
	v_add_co_u32_e64 v18, s[4:5], s16, v6
	v_addc_co_u32_e32 v13, vcc, -1, v7, vcc
	s_nop 0
	v_addc_co_u32_e64 v19, s[4:5], -1, v7, s[4:5]
	v_add_co_u32_e64 v20, s[4:5], s13, v6
	s_nop 1
	v_addc_co_u32_e64 v21, s[4:5], 0, v7, s[4:5]
	v_add_co_u32_e64 v22, s[4:5], s17, v6
	s_nop 1
	v_addc_co_u32_e64 v23, s[4:5], 0, v7, s[4:5]
	v_add_co_u32_e64 v24, s[4:5], s18, v6
	s_nop 1
	v_addc_co_u32_e64 v25, s[4:5], 0, v7, s[4:5]
	global_load_dword v82, v[14:15], off
	global_load_dword v84, v[16:17], off
	global_load_dword v86, v[12:13], off
	global_load_dword v88, v[18:19], off
	global_load_dword v90, v[20:21], off
	global_load_dword v92, v[22:23], off
	global_load_dword v94, v[24:25], off
	v_lshl_add_u64 v[6:7], v[6:7], 0, s[10:11]
	ds_read_b128 v[12:15], v11 offset:288
	ds_read_b128 v[16:19], v11 offset:800
	ds_read_b128 v[20:23], v11 offset:1312
	ds_read_b128 v[24:27], v11 offset:1824
	ds_read_b128 v[28:31], v11 offset:304
	ds_read_b128 v[32:35], v11 offset:816
	ds_read_b128 v[36:39], v11 offset:1328
	ds_read_b128 v[40:43], v11 offset:1840
	s_waitcnt lgkmcnt(6)
	v_mov_b32_e32 v60, v16
	v_mov_b32_e32 v61, v12
	s_waitcnt lgkmcnt(4)
	v_mov_b32_e32 v62, v24
	v_mov_b32_e32 v63, v20
	v_mov_b32_e32 v12, v17
	v_mov_b32_e32 v20, v25
	v_mov_b32_e32 v16, v18
	v_mov_b32_e32 v17, v14
	v_mov_b32_e32 v14, v19
	v_mov_b32_e32 v18, v26
	v_mov_b32_e32 v19, v22
	v_mov_b32_e32 v22, v27
	s_waitcnt lgkmcnt(2)
	v_mov_b32_e32 v24, v32
	v_mov_b32_e32 v25, v28
	s_waitcnt lgkmcnt(0)
	v_mov_b32_e32 v26, v40
	v_mov_b32_e32 v27, v36
	v_mov_b32_e32 v28, v33
	v_mov_b32_e32 v36, v41
	v_mov_b32_e32 v32, v34
	v_mov_b32_e32 v33, v30
	v_mov_b32_e32 v30, v35
	v_mov_b32_e32 v34, v42
	v_mov_b32_e32 v35, v38
	v_mov_b32_e32 v38, v43
	s_waitcnt vmcnt(20)
	v_pk_fma_f32 v[4:5], v[50:51], v[60:61], v[4:5] op_sel_hi:[0,1,1]
	v_pk_fma_f32 v[0:1], v[50:51], v[62:63], v[0:1] op_sel_hi:[0,1,1]
	v_pk_fma_f32 v[4:5], v[46:47], v[12:13], v[4:5] op_sel_hi:[0,1,1]
	v_pk_fma_f32 v[0:1], v[46:47], v[20:21], v[0:1] op_sel_hi:[0,1,1]
	v_pk_fma_f32 v[4:5], v[48:49], v[16:17], v[4:5] op_sel_hi:[0,1,1]
	v_pk_fma_f32 v[0:1], v[48:49], v[18:19], v[0:1] op_sel_hi:[0,1,1]
	s_waitcnt vmcnt(19)
	v_pk_fma_f32 v[4:5], v[52:53], v[14:15], v[4:5] op_sel_hi:[0,1,1]
	v_pk_fma_f32 v[0:1], v[52:53], v[22:23], v[0:1] op_sel_hi:[0,1,1]
	v_pk_fma_f32 v[4:5], v[44:45], v[24:25], v[4:5] op_sel_hi:[0,1,1]
	v_pk_fma_f32 v[0:1], v[44:45], v[26:27], v[0:1] op_sel_hi:[0,1,1]
	s_waitcnt vmcnt(18)
	v_pk_fma_f32 v[4:5], v[54:55], v[28:29], v[4:5] op_sel_hi:[0,1,1]
	v_pk_fma_f32 v[0:1], v[54:55], v[36:37], v[0:1] op_sel_hi:[0,1,1]
	s_waitcnt vmcnt(17)
	v_pk_fma_f32 v[4:5], v[56:57], v[32:33], v[4:5] op_sel_hi:[0,1,1]
	v_pk_fma_f32 v[0:1], v[56:57], v[34:35], v[0:1] op_sel_hi:[0,1,1]
	s_waitcnt vmcnt(16)
	v_pk_fma_f32 v[4:5], v[58:59], v[30:31], v[4:5] op_sel_hi:[0,1,1]
	v_pk_fma_f32 v[0:1], v[58:59], v[38:39], v[0:1] op_sel_hi:[0,1,1]
	v_add_co_u32_e64 v14, s[4:5], s14, v6
	v_add_co_u32_e32 v12, vcc, 0xfffd0000, v6
	s_nop 0
	v_addc_co_u32_e64 v15, s[4:5], -1, v7, s[4:5]
	v_add_co_u32_e64 v16, s[4:5], s15, v6
	global_load_dword v44, v[6:7], off
	s_nop 0
	v_addc_co_u32_e64 v17, s[4:5], -1, v7, s[4:5]
	v_add_co_u32_e64 v18, s[4:5], s16, v6
	v_addc_co_u32_e32 v13, vcc, -1, v7, vcc
	s_nop 0
	v_addc_co_u32_e64 v19, s[4:5], -1, v7, s[4:5]
	v_add_co_u32_e64 v20, s[4:5], s13, v6
	s_nop 1
	v_addc_co_u32_e64 v21, s[4:5], 0, v7, s[4:5]
	v_add_co_u32_e64 v22, s[4:5], s17, v6
	s_nop 1
	v_addc_co_u32_e64 v23, s[4:5], 0, v7, s[4:5]
	v_add_co_u32_e64 v24, s[4:5], s18, v6
	s_nop 1
	v_addc_co_u32_e64 v25, s[4:5], 0, v7, s[4:5]
	global_load_dword v46, v[14:15], off
	global_load_dword v48, v[16:17], off
	global_load_dword v50, v[12:13], off
	global_load_dword v52, v[18:19], off
	global_load_dword v54, v[20:21], off
	global_load_dword v56, v[22:23], off
	global_load_dword v58, v[24:25], off
	v_lshl_add_u64 v[6:7], v[6:7], 0, s[10:11]
	ds_read_b128 v[12:15], v11 offset:320
	ds_read_b128 v[16:19], v11 offset:832
	ds_read_b128 v[20:23], v11 offset:1344
	ds_read_b128 v[24:27], v11 offset:1856
	ds_read_b128 v[28:31], v11 offset:336
	ds_read_b128 v[32:35], v11 offset:848
	ds_read_b128 v[36:39], v11 offset:1360
	ds_read_b128 v[40:43], v11 offset:1872
	s_waitcnt lgkmcnt(6)
; DI void ada_partials(const P& p, LAS unsigned char* L) {
;     ...
;         float a0 = 0.f, a1 = 0.f, a2 = 0.f, a3 = 0.f;
; #pragma unroll 8
;         for (int k = 0; k < 128; ++k) { const float wv = w[(size_t)k * MODW]; a0 += condl[k] * wv; a1 += condl[128 + k] * wv; a2 += condl[256 + k] * wv; a3 += condl[384 + k] * wv; }
	v_mov_b32_e32 v60, v16
	v_mov_b32_e32 v61, v12
	s_waitcnt lgkmcnt(4)
	v_mov_b32_e32 v62, v24
	v_mov_b32_e32 v63, v20
	v_mov_b32_e32 v12, v17
	v_mov_b32_e32 v20, v25
	v_mov_b32_e32 v16, v18
	v_mov_b32_e32 v17, v14
	v_mov_b32_e32 v14, v19
	v_mov_b32_e32 v18, v26
	v_mov_b32_e32 v19, v22
	v_mov_b32_e32 v22, v27
	s_waitcnt lgkmcnt(2)
	v_mov_b32_e32 v24, v32
	v_mov_b32_e32 v25, v28
	s_waitcnt lgkmcnt(0)
	v_mov_b32_e32 v26, v40
	v_mov_b32_e32 v27, v36
	v_mov_b32_e32 v28, v33
	v_mov_b32_e32 v36, v41
	v_mov_b32_e32 v32, v34
	v_mov_b32_e32 v33, v30
	v_mov_b32_e32 v30, v35
	v_mov_b32_e32 v34, v42
	v_mov_b32_e32 v35, v38
	v_mov_b32_e32 v38, v43
	s_waitcnt vmcnt(20)
	v_pk_fma_f32 v[4:5], v[70:71], v[60:61], v[4:5] op_sel_hi:[0,1,1]
	v_pk_fma_f32 v[0:1], v[70:71], v[62:63], v[0:1] op_sel_hi:[0,1,1]
	v_pk_fma_f32 v[4:5], v[66:67], v[12:13], v[4:5] op_sel_hi:[0,1,1]
	v_pk_fma_f32 v[0:1], v[66:67], v[20:21], v[0:1] op_sel_hi:[0,1,1]
	v_pk_fma_f32 v[4:5], v[68:69], v[16:17], v[4:5] op_sel_hi:[0,1,1]
	v_pk_fma_f32 v[0:1], v[68:69], v[18:19], v[0:1] op_sel_hi:[0,1,1]
	s_waitcnt vmcnt(19)
	v_pk_fma_f32 v[4:5], v[72:73], v[14:15], v[4:5] op_sel_hi:[0,1,1]
	v_pk_fma_f32 v[0:1], v[72:73], v[22:23], v[0:1] op_sel_hi:[0,1,1]
	v_pk_fma_f32 v[4:5], v[64:65], v[24:25], v[4:5] op_sel_hi:[0,1,1]
	v_pk_fma_f32 v[0:1], v[64:65], v[26:27], v[0:1] op_sel_hi:[0,1,1]
	s_waitcnt vmcnt(18)
	v_pk_fma_f32 v[4:5], v[74:75], v[28:29], v[4:5] op_sel_hi:[0,1,1]
	v_pk_fma_f32 v[0:1], v[74:75], v[36:37], v[0:1] op_sel_hi:[0,1,1]
	s_waitcnt vmcnt(17)
	v_pk_fma_f32 v[4:5], v[76:77], v[32:33], v[4:5] op_sel_hi:[0,1,1]
	v_pk_fma_f32 v[0:1], v[76:77], v[34:35], v[0:1] op_sel_hi:[0,1,1]
	s_waitcnt vmcnt(16)
	v_pk_fma_f32 v[4:5], v[78:79], v[30:31], v[4:5] op_sel_hi:[0,1,1]
	v_pk_fma_f32 v[0:1], v[78:79], v[38:39], v[0:1] op_sel_hi:[0,1,1]
	v_add_co_u32_e64 v14, s[4:5], s14, v6
	v_add_co_u32_e32 v12, vcc, 0xfffd0000, v6
	s_nop 0
	v_addc_co_u32_e64 v15, s[4:5], -1, v7, s[4:5]
	v_add_co_u32_e64 v16, s[4:5], s15, v6
	global_load_dword v64, v[6:7], off
	s_nop 0
	v_addc_co_u32_e64 v17, s[4:5], -1, v7, s[4:5]
	v_add_co_u32_e64 v18, s[4:5], s16, v6
	v_addc_co_u32_e32 v13, vcc, -1, v7, vcc
	s_nop 0
	v_addc_co_u32_e64 v19, s[4:5], -1, v7, s[4:5]
	v_add_co_u32_e64 v20, s[4:5], s13, v6
	s_nop 1
	v_addc_co_u32_e64 v21, s[4:5], 0, v7, s[4:5]
	v_add_co_u32_e64 v22, s[4:5], s17, v6
	s_nop 1
	v_addc_co_u32_e64 v23, s[4:5], 0, v7, s[4:5]
	v_add_co_u32_e64 v24, s[4:5], s18, v6
	s_nop 1
	v_addc_co_u32_e64 v25, s[4:5], 0, v7, s[4:5]
	global_load_dword v66, v[14:15], off
	global_load_dword v68, v[16:17], off
	global_load_dword v70, v[12:13], off
	global_load_dword v72, v[18:19], off
	global_load_dword v74, v[20:21], off
	global_load_dword v76, v[22:23], off
	global_load_dword v78, v[24:25], off
	v_lshl_add_u64 v[6:7], v[6:7], 0, s[10:11]
	ds_read_b128 v[12:15], v11 offset:352
	ds_read_b128 v[16:19], v11 offset:864
	ds_read_b128 v[20:23], v11 offset:1376
	ds_read_b128 v[24:27], v11 offset:1888
	ds_read_b128 v[28:31], v11 offset:368
	ds_read_b128 v[32:35], v11 offset:880
	ds_read_b128 v[36:39], v11 offset:1392
	ds_read_b128 v[40:43], v11 offset:1904
	s_waitcnt lgkmcnt(6)
	v_mov_b32_e32 v60, v16
	v_mov_b32_e32 v61, v12
	s_waitcnt lgkmcnt(4)
	v_mov_b32_e32 v62, v24
	v_mov_b32_e32 v63, v20
	v_mov_b32_e32 v12, v17
	v_mov_b32_e32 v20, v25
	v_mov_b32_e32 v16, v18
	v_mov_b32_e32 v17, v14
	v_mov_b32_e32 v14, v19
	v_mov_b32_e32 v18, v26
	v_mov_b32_e32 v19, v22
	v_mov_b32_e32 v22, v27
	s_waitcnt lgkmcnt(2)
	v_mov_b32_e32 v24, v32
	v_mov_b32_e32 v25, v28
	s_waitcnt lgkmcnt(0)
	v_mov_b32_e32 v26, v40
	v_mov_b32_e32 v27, v36
	v_mov_b32_e32 v28, v33
	v_mov_b32_e32 v36, v41
	v_mov_b32_e32 v32, v34
	v_mov_b32_e32 v33, v30
	v_mov_b32_e32 v30, v35
	v_mov_b32_e32 v34, v42
	v_mov_b32_e32 v35, v38
	v_mov_b32_e32 v38, v43
	s_waitcnt vmcnt(20)
	v_pk_fma_f32 v[4:5], v[86:87], v[60:61], v[4:5] op_sel_hi:[0,1,1]
	v_pk_fma_f32 v[0:1], v[86:87], v[62:63], v[0:1] op_sel_hi:[0,1,1]
	v_pk_fma_f32 v[4:5], v[82:83], v[12:13], v[4:5] op_sel_hi:[0,1,1]
	v_pk_fma_f32 v[0:1], v[82:83], v[20:21], v[0:1] op_sel_hi:[0,1,1]
	v_pk_fma_f32 v[4:5], v[84:85], v[16:17], v[4:5] op_sel_hi:[0,1,1]
	v_pk_fma_f32 v[0:1], v[84:85], v[18:19], v[0:1] op_sel_hi:[0,1,1]
	s_waitcnt vmcnt(19)
	v_pk_fma_f32 v[4:5], v[88:89], v[14:15], v[4:5] op_sel_hi:[0,1,1]
	v_pk_fma_f32 v[0:1], v[88:89], v[22:23], v[0:1] op_sel_hi:[0,1,1]
	v_pk_fma_f32 v[4:5], v[80:81], v[24:25], v[4:5] op_sel_hi:[0,1,1]
	v_pk_fma_f32 v[0:1], v[80:81], v[26:27], v[0:1] op_sel_hi:[0,1,1]
	s_waitcnt vmcnt(18)
	v_pk_fma_f32 v[4:5], v[90:91], v[28:29], v[4:5] op_sel_hi:[0,1,1]
	v_pk_fma_f32 v[0:1], v[90:91], v[36:37], v[0:1] op_sel_hi:[0,1,1]
	s_waitcnt vmcnt(17)
	v_pk_fma_f32 v[4:5], v[92:93], v[32:33], v[4:5] op_sel_hi:[0,1,1]
	v_pk_fma_f32 v[0:1], v[92:93], v[34:35], v[0:1] op_sel_hi:[0,1,1]
	s_waitcnt vmcnt(16)
	v_pk_fma_f32 v[4:5], v[94:95], v[30:31], v[4:5] op_sel_hi:[0,1,1]
	v_pk_fma_f32 v[0:1], v[94:95], v[38:39], v[0:1] op_sel_hi:[0,1,1]
	v_add_co_u32_e64 v14, s[4:5], s14, v6
	v_add_co_u32_e32 v12, vcc, 0xfffd0000, v6
	s_nop 0
	v_addc_co_u32_e64 v15, s[4:5], -1, v7, s[4:5]
	v_add_co_u32_e64 v16, s[4:5], s15, v6
	global_load_dword v80, v[6:7], off
	s_nop 0
	v_addc_co_u32_e64 v17, s[4:5], -1, v7, s[4:5]
	v_add_co_u32_e64 v18, s[4:5], s16, v6
	v_addc_co_u32_e32 v13, vcc, -1, v7, vcc
	s_nop 0
	v_addc_co_u32_e64 v19, s[4:5], -1, v7, s[4:5]
	v_add_co_u32_e64 v20, s[4:5], s13, v6
	s_nop 1
	v_addc_co_u32_e64 v21, s[4:5], 0, v7, s[4:5]
	v_add_co_u32_e64 v22, s[4:5], s17, v6
	s_nop 1
	v_addc_co_u32_e64 v23, s[4:5], 0, v7, s[4:5]
	v_add_co_u32_e64 v24, s[4:5], s18, v6
	s_nop 1
	v_addc_co_u32_e64 v25, s[4:5], 0, v7, s[4:5]
	global_load_dword v82, v[14:15], off
	global_load_dword v84, v[16:17], off
	global_load_dword v86, v[12:13], off
	global_load_dword v88, v[18:19], off
	global_load_dword v90, v[20:21], off
	global_load_dword v92, v[22:23], off
	global_load_dword v94, v[24:25], off
	v_lshl_add_u64 v[6:7], v[6:7], 0, s[10:11]
	ds_read_b128 v[12:15], v11 offset:384
	ds_read_b128 v[16:19], v11 offset:896
	ds_read_b128 v[20:23], v11 offset:1408
	ds_read_b128 v[24:27], v11 offset:1920
	ds_read_b128 v[28:31], v11 offset:400
	ds_read_b128 v[32:35], v11 offset:912
	ds_read_b128 v[36:39], v11 offset:1424
	ds_read_b128 v[40:43], v11 offset:1936
	s_waitcnt lgkmcnt(6)
; DI void ada_partials(const P& p, LAS unsigned char* L) {
;     ...
;         float a0 = 0.f, a1 = 0.f, a2 = 0.f, a3 = 0.f;
; #pragma unroll 8
;         for (int k = 0; k < 128; ++k) { const float wv = w[(size_t)k * MODW]; a0 += condl[k] * wv; a1 += condl[128 + k] * wv; a2 += condl[256 + k] * wv; a3 += condl[384 + k] * wv; }
	v_mov_b32_e32 v60, v16
	v_mov_b32_e32 v61, v12
	s_waitcnt lgkmcnt(4)
	v_mov_b32_e32 v62, v24
	v_mov_b32_e32 v63, v20
	v_mov_b32_e32 v12, v17
	v_mov_b32_e32 v20, v25
	v_mov_b32_e32 v16, v18
	v_mov_b32_e32 v17, v14
	v_mov_b32_e32 v14, v19
	v_mov_b32_e32 v18, v26
	v_mov_b32_e32 v19, v22
	v_mov_b32_e32 v22, v27
	s_waitcnt lgkmcnt(2)
	v_mov_b32_e32 v24, v32
	v_mov_b32_e32 v25, v28
	s_waitcnt lgkmcnt(0)
	v_mov_b32_e32 v26, v40
	v_mov_b32_e32 v27, v36
	v_mov_b32_e32 v28, v33
	v_mov_b32_e32 v36, v41
	v_mov_b32_e32 v32, v34
	v_mov_b32_e32 v33, v30
	v_mov_b32_e32 v30, v35
	v_mov_b32_e32 v34, v42
	v_mov_b32_e32 v35, v38
	v_mov_b32_e32 v38, v43
	s_waitcnt vmcnt(20)
	v_pk_fma_f32 v[4:5], v[50:51], v[60:61], v[4:5] op_sel_hi:[0,1,1]
	v_pk_fma_f32 v[0:1], v[50:51], v[62:63], v[0:1] op_sel_hi:[0,1,1]
	v_pk_fma_f32 v[4:5], v[46:47], v[12:13], v[4:5] op_sel_hi:[0,1,1]
	v_pk_fma_f32 v[0:1], v[46:47], v[20:21], v[0:1] op_sel_hi:[0,1,1]
	v_pk_fma_f32 v[4:5], v[48:49], v[16:17], v[4:5] op_sel_hi:[0,1,1]
	v_pk_fma_f32 v[0:1], v[48:49], v[18:19], v[0:1] op_sel_hi:[0,1,1]
	s_waitcnt vmcnt(19)
	v_pk_fma_f32 v[4:5], v[52:53], v[14:15], v[4:5] op_sel_hi:[0,1,1]
	v_pk_fma_f32 v[0:1], v[52:53], v[22:23], v[0:1] op_sel_hi:[0,1,1]
	v_pk_fma_f32 v[4:5], v[44:45], v[24:25], v[4:5] op_sel_hi:[0,1,1]
	v_pk_fma_f32 v[0:1], v[44:45], v[26:27], v[0:1] op_sel_hi:[0,1,1]
	s_waitcnt vmcnt(18)
	v_pk_fma_f32 v[4:5], v[54:55], v[28:29], v[4:5] op_sel_hi:[0,1,1]
	v_pk_fma_f32 v[0:1], v[54:55], v[36:37], v[0:1] op_sel_hi:[0,1,1]
	s_waitcnt vmcnt(17)
	v_pk_fma_f32 v[4:5], v[56:57], v[32:33], v[4:5] op_sel_hi:[0,1,1]
	v_pk_fma_f32 v[0:1], v[56:57], v[34:35], v[0:1] op_sel_hi:[0,1,1]
	s_waitcnt vmcnt(16)
	v_pk_fma_f32 v[4:5], v[58:59], v[30:31], v[4:5] op_sel_hi:[0,1,1]
	v_pk_fma_f32 v[0:1], v[58:59], v[38:39], v[0:1] op_sel_hi:[0,1,1]
	v_add_co_u32_e64 v14, s[4:5], s14, v6
	v_add_co_u32_e32 v12, vcc, 0xfffd0000, v6
	s_nop 0
	v_addc_co_u32_e64 v15, s[4:5], -1, v7, s[4:5]
	v_add_co_u32_e64 v16, s[4:5], s15, v6
	global_load_dword v44, v[6:7], off
	s_nop 0
	v_addc_co_u32_e64 v17, s[4:5], -1, v7, s[4:5]
	v_add_co_u32_e64 v18, s[4:5], s16, v6
	v_addc_co_u32_e32 v13, vcc, -1, v7, vcc
	s_nop 0
	v_addc_co_u32_e64 v19, s[4:5], -1, v7, s[4:5]
	v_add_co_u32_e64 v20, s[4:5], s13, v6
	s_nop 1
	v_addc_co_u32_e64 v21, s[4:5], 0, v7, s[4:5]
	v_add_co_u32_e64 v22, s[4:5], s17, v6
	s_nop 1
	v_addc_co_u32_e64 v23, s[4:5], 0, v7, s[4:5]
	v_add_co_u32_e64 v24, s[4:5], s18, v6
	s_nop 1
	v_addc_co_u32_e64 v25, s[4:5], 0, v7, s[4:5]
	global_load_dword v46, v[14:15], off
	global_load_dword v48, v[16:17], off
	global_load_dword v50, v[12:13], off
	global_load_dword v52, v[18:19], off
	global_load_dword v54, v[20:21], off
	global_load_dword v56, v[22:23], off
	global_load_dword v58, v[24:25], off
	v_lshl_add_u64 v[6:7], v[6:7], 0, s[10:11]
	ds_read_b128 v[12:15], v11 offset:416
	ds_read_b128 v[16:19], v11 offset:928
	ds_read_b128 v[20:23], v11 offset:1440
	ds_read_b128 v[24:27], v11 offset:1952
	ds_read_b128 v[28:31], v11 offset:432
	ds_read_b128 v[32:35], v11 offset:944
	ds_read_b128 v[36:39], v11 offset:1456
	ds_read_b128 v[40:43], v11 offset:1968
	s_waitcnt lgkmcnt(6)
	v_mov_b32_e32 v60, v16
	v_mov_b32_e32 v61, v12
	s_waitcnt lgkmcnt(4)
	v_mov_b32_e32 v62, v24
	v_mov_b32_e32 v63, v20
	v_mov_b32_e32 v12, v17
	v_mov_b32_e32 v20, v25
	v_mov_b32_e32 v16, v18
	v_mov_b32_e32 v17, v14
	v_mov_b32_e32 v14, v19
	v_mov_b32_e32 v18, v26
	v_mov_b32_e32 v19, v22
	v_mov_b32_e32 v22, v27
	s_waitcnt lgkmcnt(2)
	v_mov_b32_e32 v24, v32
	v_mov_b32_e32 v25, v28
	s_waitcnt lgkmcnt(0)
	v_mov_b32_e32 v26, v40
	v_mov_b32_e32 v27, v36
	v_mov_b32_e32 v28, v33
	v_mov_b32_e32 v36, v41
	v_mov_b32_e32 v32, v34
	v_mov_b32_e32 v33, v30
	v_mov_b32_e32 v30, v35
	v_mov_b32_e32 v34, v42
	v_mov_b32_e32 v35, v38
	v_mov_b32_e32 v38, v43
	s_waitcnt vmcnt(20)
	v_pk_fma_f32 v[4:5], v[70:71], v[60:61], v[4:5] op_sel_hi:[0,1,1]
	v_pk_fma_f32 v[0:1], v[70:71], v[62:63], v[0:1] op_sel_hi:[0,1,1]
	v_pk_fma_f32 v[4:5], v[66:67], v[12:13], v[4:5] op_sel_hi:[0,1,1]
	v_pk_fma_f32 v[0:1], v[66:67], v[20:21], v[0:1] op_sel_hi:[0,1,1]
	v_pk_fma_f32 v[4:5], v[68:69], v[16:17], v[4:5] op_sel_hi:[0,1,1]
	v_pk_fma_f32 v[0:1], v[68:69], v[18:19], v[0:1] op_sel_hi:[0,1,1]
	s_waitcnt vmcnt(19)
	v_pk_fma_f32 v[4:5], v[72:73], v[14:15], v[4:5] op_sel_hi:[0,1,1]
	v_pk_fma_f32 v[0:1], v[72:73], v[22:23], v[0:1] op_sel_hi:[0,1,1]
	v_pk_fma_f32 v[4:5], v[64:65], v[24:25], v[4:5] op_sel_hi:[0,1,1]
	v_pk_fma_f32 v[0:1], v[64:65], v[26:27], v[0:1] op_sel_hi:[0,1,1]
	s_waitcnt vmcnt(18)
	v_pk_fma_f32 v[4:5], v[74:75], v[28:29], v[4:5] op_sel_hi:[0,1,1]
	v_pk_fma_f32 v[0:1], v[74:75], v[36:37], v[0:1] op_sel_hi:[0,1,1]
	s_waitcnt vmcnt(17)
	v_pk_fma_f32 v[4:5], v[76:77], v[32:33], v[4:5] op_sel_hi:[0,1,1]
	v_pk_fma_f32 v[0:1], v[76:77], v[34:35], v[0:1] op_sel_hi:[0,1,1]
	s_waitcnt vmcnt(16)
; DI void ada_partials(const P& p, LAS unsigned char* L) {
;     ...
; #pragma unroll 8
;         for (int k = 0; k < 128; ++k) { const float wv = w[(size_t)k * MODW]; a0 += condl[k] * wv; a1 += condl[128 + k] * wv; a2 += condl[256 + k] * wv; a3 += condl[384 + k] * wv; }
;         float* o = modp + ((size_t)(ks * 2 + l) * 4) * MODW + col;
;         o[0] = a0; o[MODW] = a1; o[2 * MODW] = a2; o[3 * MODW] = a3;
	v_pk_fma_f32 v[4:5], v[78:79], v[30:31], v[4:5] op_sel_hi:[0,1,1]
	v_pk_fma_f32 v[0:1], v[78:79], v[38:39], v[0:1] op_sel_hi:[0,1,1]
	ds_read_b128 v[12:15], v11 offset:448
	ds_read_b128 v[16:19], v11 offset:960
	ds_read_b128 v[20:23], v11 offset:1472
	ds_read_b128 v[24:27], v11 offset:1984
	ds_read_b128 v[28:31], v11 offset:464
	ds_read_b128 v[32:35], v11 offset:976
	ds_read_b128 v[36:39], v11 offset:1488
	ds_read_b128 v[40:43], v11 offset:2000
	s_waitcnt lgkmcnt(6)
	v_mov_b32_e32 v60, v16
	v_mov_b32_e32 v61, v12
	s_waitcnt lgkmcnt(4)
	v_mov_b32_e32 v62, v24
	v_mov_b32_e32 v63, v20
	v_mov_b32_e32 v12, v17
	v_mov_b32_e32 v20, v25
	v_mov_b32_e32 v16, v18
	v_mov_b32_e32 v17, v14
	v_mov_b32_e32 v14, v19
	v_mov_b32_e32 v18, v26
	v_mov_b32_e32 v19, v22
	v_mov_b32_e32 v22, v27
	s_waitcnt lgkmcnt(2)
	v_mov_b32_e32 v24, v32
	v_mov_b32_e32 v25, v28
	s_waitcnt lgkmcnt(0)
	v_mov_b32_e32 v26, v40
	v_mov_b32_e32 v27, v36
	v_mov_b32_e32 v28, v33
	v_mov_b32_e32 v36, v41
	v_mov_b32_e32 v32, v34
	v_mov_b32_e32 v33, v30
	v_mov_b32_e32 v30, v35
	v_mov_b32_e32 v34, v42
	v_mov_b32_e32 v35, v38
	v_mov_b32_e32 v38, v43
	s_waitcnt vmcnt(12)
	v_pk_fma_f32 v[4:5], v[86:87], v[60:61], v[4:5] op_sel_hi:[0,1,1]
	v_pk_fma_f32 v[0:1], v[86:87], v[62:63], v[0:1] op_sel_hi:[0,1,1]
	v_pk_fma_f32 v[4:5], v[82:83], v[12:13], v[4:5] op_sel_hi:[0,1,1]
	v_pk_fma_f32 v[0:1], v[82:83], v[20:21], v[0:1] op_sel_hi:[0,1,1]
	v_pk_fma_f32 v[4:5], v[84:85], v[16:17], v[4:5] op_sel_hi:[0,1,1]
	v_pk_fma_f32 v[0:1], v[84:85], v[18:19], v[0:1] op_sel_hi:[0,1,1]
	s_waitcnt vmcnt(11)
	v_pk_fma_f32 v[4:5], v[88:89], v[14:15], v[4:5] op_sel_hi:[0,1,1]
	v_pk_fma_f32 v[0:1], v[88:89], v[22:23], v[0:1] op_sel_hi:[0,1,1]
	v_pk_fma_f32 v[4:5], v[80:81], v[24:25], v[4:5] op_sel_hi:[0,1,1]
	v_pk_fma_f32 v[0:1], v[80:81], v[26:27], v[0:1] op_sel_hi:[0,1,1]
	s_waitcnt vmcnt(10)
	v_pk_fma_f32 v[4:5], v[90:91], v[28:29], v[4:5] op_sel_hi:[0,1,1]
	v_pk_fma_f32 v[0:1], v[90:91], v[36:37], v[0:1] op_sel_hi:[0,1,1]
	s_waitcnt vmcnt(9)
	v_pk_fma_f32 v[4:5], v[92:93], v[32:33], v[4:5] op_sel_hi:[0,1,1]
	v_pk_fma_f32 v[0:1], v[92:93], v[34:35], v[0:1] op_sel_hi:[0,1,1]
	s_waitcnt vmcnt(8)
	v_pk_fma_f32 v[4:5], v[94:95], v[30:31], v[4:5] op_sel_hi:[0,1,1]
	v_pk_fma_f32 v[0:1], v[94:95], v[38:39], v[0:1] op_sel_hi:[0,1,1]
	ds_read_b128 v[12:15], v11 offset:480
	ds_read_b128 v[16:19], v11 offset:992
	ds_read_b128 v[20:23], v11 offset:1504
	ds_read_b128 v[24:27], v11 offset:2016
	ds_read_b128 v[28:31], v11 offset:496
	ds_read_b128 v[32:35], v11 offset:1008
	ds_read_b128 v[36:39], v11 offset:1520
	ds_read_b128 v[40:43], v11 offset:2032
	s_waitcnt lgkmcnt(6)
	v_mov_b32_e32 v60, v16
	v_mov_b32_e32 v61, v12
	s_waitcnt lgkmcnt(4)
	v_mov_b32_e32 v62, v24
	v_mov_b32_e32 v63, v20
	v_mov_b32_e32 v12, v17
	v_mov_b32_e32 v20, v25
	v_mov_b32_e32 v16, v18
	v_mov_b32_e32 v17, v14
	v_mov_b32_e32 v14, v19
	v_mov_b32_e32 v18, v26
	v_mov_b32_e32 v19, v22
	v_mov_b32_e32 v22, v27
	s_waitcnt lgkmcnt(2)
	v_mov_b32_e32 v24, v32
	v_mov_b32_e32 v25, v28
	s_waitcnt lgkmcnt(0)
	v_mov_b32_e32 v26, v40
	v_mov_b32_e32 v27, v36
	v_mov_b32_e32 v28, v33
	v_mov_b32_e32 v36, v41
	v_mov_b32_e32 v32, v34
	v_mov_b32_e32 v33, v30
	v_mov_b32_e32 v30, v35
	v_mov_b32_e32 v34, v42
	v_mov_b32_e32 v35, v38
	v_mov_b32_e32 v38, v43
	s_waitcnt vmcnt(4)
	v_pk_fma_f32 v[4:5], v[50:51], v[60:61], v[4:5] op_sel_hi:[0,1,1]
	v_pk_fma_f32 v[0:1], v[50:51], v[62:63], v[0:1] op_sel_hi:[0,1,1]
	v_pk_fma_f32 v[4:5], v[46:47], v[12:13], v[4:5] op_sel_hi:[0,1,1]
	v_pk_fma_f32 v[0:1], v[46:47], v[20:21], v[0:1] op_sel_hi:[0,1,1]
	v_pk_fma_f32 v[4:5], v[48:49], v[16:17], v[4:5] op_sel_hi:[0,1,1]
	v_pk_fma_f32 v[0:1], v[48:49], v[18:19], v[0:1] op_sel_hi:[0,1,1]
	s_waitcnt vmcnt(3)
	v_pk_fma_f32 v[4:5], v[52:53], v[14:15], v[4:5] op_sel_hi:[0,1,1]
	v_pk_fma_f32 v[0:1], v[52:53], v[22:23], v[0:1] op_sel_hi:[0,1,1]
	v_pk_fma_f32 v[4:5], v[44:45], v[24:25], v[4:5] op_sel_hi:[0,1,1]
	v_pk_fma_f32 v[0:1], v[44:45], v[26:27], v[0:1] op_sel_hi:[0,1,1]
	s_waitcnt vmcnt(2)
	v_pk_fma_f32 v[4:5], v[54:55], v[28:29], v[4:5] op_sel_hi:[0,1,1]
	v_pk_fma_f32 v[0:1], v[54:55], v[36:37], v[0:1] op_sel_hi:[0,1,1]
	s_waitcnt vmcnt(1)
	v_pk_fma_f32 v[4:5], v[56:57], v[32:33], v[4:5] op_sel_hi:[0,1,1]
	v_pk_fma_f32 v[0:1], v[56:57], v[34:35], v[0:1] op_sel_hi:[0,1,1]
	s_waitcnt vmcnt(0)
	v_pk_fma_f32 v[4:5], v[58:59], v[30:31], v[4:5] op_sel_hi:[0,1,1]
	v_pk_fma_f32 v[0:1], v[58:59], v[38:39], v[0:1] op_sel_hi:[0,1,1]
	s_lshl_b32 s4, s21, 1
	s_add_i32 s4, s4, s20
	s_mul_hi_i32 s5, s4, 0x30000
	s_mul_i32 s4, s4, 0x30000
	s_add_u32 s4, s6, s4
	s_addc_u32 s5, s7, s5
	v_lshl_add_u64 v[2:3], v[2:3], 2, s[4:5]
	v_add_co_u32_e32 v6, vcc, 0xc000, v2
	global_store_dword v[2:3], v5, off
	s_nop 0
	v_addc_co_u32_e32 v7, vcc, 0, v3, vcc
	global_store_dword v[6:7], v4, off
	v_add_co_u32_e32 v4, vcc, 0x18000, v2
	s_add_i32 s19, s19, s86
	s_nop 0
	v_addc_co_u32_e32 v5, vcc, 0, v3, vcc
	v_add_co_u32_e32 v2, vcc, 0x24000, v2
	s_cmpk_gt_i32 s19, 0x2ff
	s_nop 0
	v_addc_co_u32_e32 v3, vcc, 0, v3, vcc
	global_store_dword v[4:5], v1, off
	global_store_dword v[2:3], v0, off
	s_cbranch_scc0 .LBB0_46
